# XCD-aware tile swizzle for PH6/PH8/PH9 (8m x 8n tile block per XCD) on top of LDS-DMA GEMMs
# speedup vs baseline: 1.0677x; 1.0169x over previous
.LBB0_1184:
	s_or_b64 exec, exec, s[0:1]
	v_readlane_b32 s0, v207, 0
	v_readlane_b32 s1, v207, 1
	s_and_b64 s[0:1], s[0:1], exec
	s_movk_i32 s0, 0x440
	s_cselect_b32 s0, 0x400, s0
	s_cmp_ge_i32 s97, s0
	s_waitcnt lgkmcnt(0)
	s_barrier
	v_writelane_b32 v207, s0, 2
	s_cbranch_scc1 .LBB0_1188
	v_readlane_b32 s36, v210, 50
	v_readlane_b32 s44, v210, 58
	v_readlane_b32 s45, v210, 59
	v_readlane_b32 s46, v210, 60
	v_readlane_b32 s47, v210, 61
	v_readlane_b32 s48, v210, 62
	v_readlane_b32 s49, v210, 63
	v_readlane_b32 s50, v209, 0
	v_readlane_b32 s51, v209, 1
	v_readlane_b32 s44, v210, 2
	s_lshl_b32 s0, s60, 1
	v_readlane_b32 s42, v210, 56
	v_readlane_b32 s52, v210, 10
	v_readlane_b32 s53, v210, 11
	v_readlane_b32 s43, v210, 57
	s_add_u32 s0, s42, s0
	v_readlane_b32 s54, v210, 12
	v_readlane_b32 s55, v210, 13
	v_readlane_b32 s56, v210, 14
	v_readlane_b32 s57, v210, 15
	v_readlane_b32 s58, v210, 16
	v_readlane_b32 s59, v210, 17
	v_readlane_b32 s52, v208, 58
	s_addc_u32 s1, s43, 0
	s_lshl_b32 s2, s66, 7
	v_readlane_b32 s3, v208, 16
	s_mov_b32 s4, s97
	s_mov_b32 s61, 0x30000
	s_mov_b32 s63, 0x20000
	s_mov_b32 s10, 0x10000
	s_mov_b32 s62, 0x12000
	s_mov_b32 s57, 0x13000
	s_mov_b32 s54, 0x18000
	s_mov_b32 s55, 0x19000
	s_mov_b32 s72, 0x1a000
	s_mov_b32 s73, 0x1b000
	s_mov_b32 s74, 0x21000
	s_mov_b32 s75, 0x22000
	s_mov_b32 s76, 0x23000
	s_mov_b32 s77, 0x28000
	s_mov_b32 s78, 0x29000
	s_mov_b32 s79, 0x2a000
	s_mov_b32 s58, 0x2b000
	s_mov_b32 s56, 0x31000
	s_mov_b32 s97, 0x32000
	s_mov_b32 s9, 0x33000
	s_mov_b32 s69, 0x38000
	s_mov_b32 s60, 0x3a000
	s_mov_b32 s67, 0x39000
	v_readlane_b32 s70, v208, 62
	v_readlane_b32 s53, v208, 59
	s_mov_b32 s33, 0x3b000
	v_readlane_b32 s59, v207, 2
	v_readlane_b32 s37, v210, 51
	v_readlane_b32 s38, v210, 52
	v_readlane_b32 s39, v210, 53
	v_readlane_b32 s40, v210, 54
	v_readlane_b32 s41, v210, 55
	v_readlane_b32 s45, v210, 3
	v_readlane_b32 s46, v210, 4
	v_readlane_b32 s47, v210, 5
	v_readlane_b32 s48, v210, 6
	v_readlane_b32 s49, v210, 7
	v_readlane_b32 s50, v210, 8
	v_readlane_b32 s51, v210, 9
	v_readlane_b32 s4, v209, 2
	s_and_b32 s5, s4, 7
	s_lshr_b32 s4, s4, 3
	s_lshl_b32 s5, s5, 6
	s_or_b32 s4, s4, s5
	s_lshl_b32 s3, s4, 7

.LBB0_1296:
	s_or_b64 exec, exec, s[0:1]
	v_readlane_b32 s0, v207, 0
	v_readlane_b32 s1, v207, 1
	s_and_b64 s[0:1], s[0:1], exec
	s_movk_i32 s0, 0x1000
	s_cselect_b32 s2, s0, 0x1100
	s_cmp_ge_i32 s97, s2
	s_waitcnt lgkmcnt(0)
	s_barrier
	s_cbranch_scc1 .LBB0_1300
	s_mov_b64 s[8:9], s[42:43]
	v_readlane_b32 s36, v210, 50
	s_lshl_b32 s0, s60, 1
	v_readlane_b32 s44, v210, 58
	v_readlane_b32 s45, v210, 59
	s_add_u32 s0, s44, s0
	v_readlane_b32 s38, v210, 52
	v_readlane_b32 s39, v210, 53
	v_readlane_b32 s50, v209, 0
	v_readlane_b32 s51, v209, 1
	s_addc_u32 s1, s45, 0
	s_lshl_b32 s3, s66, 7
	v_readlane_b32 s4, v208, 16
	s_mov_b32 s5, s97
	v_readlane_b32 s37, v210, 51
	v_readlane_b32 s40, v210, 54
	v_readlane_b32 s41, v210, 55
	v_readlane_b32 s42, v210, 56
	v_readlane_b32 s43, v210, 57
	v_readlane_b32 s46, v210, 60
	v_readlane_b32 s47, v210, 61
	v_readlane_b32 s48, v210, 62
	v_readlane_b32 s49, v210, 63
	v_readlane_b32 s5, v209, 2
	s_and_b32 s6, s5, 1
	s_lshl_b32 s6, s6, 8
	s_bfe_u32 s7, s5, 0x20001
	s_lshl_b32 s7, s7, 3
	s_or_b32 s6, s6, s7
	s_bfe_u32 s7, s5, 0x30003
	s_or_b32 s6, s6, s7
	s_lshr_b32 s7, s5, 6
	s_lshl_b32 s7, s7, 5
	s_or_b32 s5, s6, s7
	s_lshl_b32 s4, s5, 7

.LBB0_1352:
	s_or_b64 exec, exec, s[0:1]
	v_readlane_b32 s0, v208, 10
	v_readlane_b32 s1, v208, 11
	s_and_b64 s[0:1], s[0:1], exec
	v_readlane_b32 s0, v207, 2
	s_cselect_b32 s6, 0x400, s0
	s_cmp_ge_i32 s97, s6
	s_movk_i32 s9, 0x4000
	s_waitcnt lgkmcnt(0)
	s_barrier
	s_cbranch_scc1 .LBB0_1363
	v_readlane_b32 s36, v210, 50
	s_lshl_b32 s0, s60, 1
	v_readlane_b32 s46, v210, 60
	v_readlane_b32 s47, v210, 61
	s_add_u32 s0, s46, s0
	s_addc_u32 s1, s47, 0
	v_readlane_b32 s7, v209, 2
	s_and_b32 s2, s7, 7
	s_lshr_b32 s7, s7, 3
	s_lshl_b32 s2, s2, 6
	s_or_b32 s7, s7, s2
	v_readlane_b32 s37, v210, 51
	v_readlane_b32 s38, v210, 52
	v_readlane_b32 s39, v210, 53
	v_readlane_b32 s40, v210, 54
	v_readlane_b32 s41, v210, 55
	v_readlane_b32 s42, v210, 56
	v_readlane_b32 s43, v210, 57
	v_readlane_b32 s44, v210, 58
	v_readlane_b32 s45, v210, 59
	v_readlane_b32 s48, v210, 62
	v_readlane_b32 s49, v210, 63
	v_readlane_b32 s50, v209, 0
	v_readlane_b32 s51, v209, 1
	s_branch .LBB0_1355
